# nt set without the in-place-overwritten streams; adds only the cq query loads of the memory attention
# speedup vs baseline: 1.0148x; 1.0018x over previous
.LBB0_961:
	s_or_b64 exec, exec, s[0:1]
	v_ashrrev_i32_e32 v0, 6, v6
	v_cmp_lt_i32_e64 s[0:1], v0, v2
	v_lshlrev_b32_e32 v0, 5, v0
	v_and_b32_e32 v7, 31, v6
	v_add3_u32 v0, v7, v1, v0
	v_ashrrev_i32_e32 v1, 31, v0
	s_lshl_b32 s4, s30, 6
	v_lshlrev_b64 v[0:1], 8, v[0:1]
	s_ashr_i32 s5, s4, 31
	v_lshl_add_u64 v[0:1], v[0:1], 0, s[4:5]
	s_and_saveexec_b64 s[4:5], s[0:1]
	s_cbranch_execz .LBB0_963
	v_readlane_b32 s14, v253, 62
	v_readlane_b32 s15, v253, 63
	v_lshrrev_b32_e32 v4, 1, v6
	v_and_b32_e32 v194, 16, v4
	v_lshl_add_u64 v[2:3], v[0:1], 1, s[14:15]
	v_lshl_add_u64 v[2:3], v[2:3], 0, v[194:195]
	global_load_dwordx4 v[116:119], v[2:3], off nt
	global_load_dwordx4 v[120:123], v[2:3], off offset:32 nt
	global_load_dwordx4 v[124:127], v[2:3], off offset:64 nt
	global_load_dwordx4 v[128:131], v[2:3], off offset:96 nt
